# phase_stat: 4 rows of loads in flight (loop unrolled by 4, vmcnt(10))
# baseline (speedup 1.0000x reference)
; __device__ __forceinline__ float wave_sum(float v) {
; #pragma unroll
;   for (int o = 32; o >= 1; o >>= 1) v += __shfl_xor(v, o);
;   return v;
; __device__ void phase_stat(const KP& p) {
;   int tid_ = threadIdx.x; asm volatile("" : "+v"(tid_));
;   const int lane = tid_ & 63, w = tid_ >> 6;
;   const bfr* hb = (const bfr*)(p.ws + OFF_HB);
;   float* rs = (float*)(p.ws + OFF_RS);
;   for (int row = p.bid * 8 + w; row < T_ROWS; row += p.nblk * 8) {
;     float ss = 0.f;
; #pragma unroll
;     for (int i = 0; i < 2; ++i) {
;       u32x4 v = *(const u32x4*)(hb + (size_t)row * DM + lane * 8 + 512 * i);
.LBB0_27:
	v_readlane_b32 s0, v255, 51
	v_readlane_b32 s1, v255, 52
	s_and_b64 vcc, exec, s[0:1]
	s_cbranch_vccz .LBB0_34
	s_waitcnt vmcnt(0)
	v_mov_b32_e32 v3, v156
	v_readlane_b32 s0, v255, 42
	s_lshl_b32 s0, s0, 3
	v_ashrrev_i32_e32 v2, 6, v3
	v_add_u32_e32 v0, s0, v2
	s_mov_b32 s1, 0x8400
	v_cmp_gt_i32_e32 vcc, s1, v0
	s_and_saveexec_b64 s[36:37], vcc
	s_cbranch_execz .LBB0_33
	v_and_b32_e32 v12, 63, v3
	v_and_b32_e32 v3, 64, v164
	v_add_u32_e32 v3, 64, v3
	v_xor_b32_e32 v4, 32, v164
	v_cmp_lt_i32_e32 vcc, v4, v3
	v_readlane_b32 s2, v255, 43
	v_readlane_b32 s3, v255, 44
	v_cndmask_b32_e32 v4, v164, v4, vcc
	v_lshlrev_b32_e32 v6, 2, v4
	v_xor_b32_e32 v4, 16, v164
	v_cmp_lt_i32_e32 vcc, v4, v3
	s_lshl_b32 s38, s2, 3
	s_ashr_i32 s1, s0, 31
	v_cndmask_b32_e32 v4, v164, v4, vcc
	v_lshlrev_b32_e32 v7, 2, v4
	v_xor_b32_e32 v4, 8, v164
	v_cmp_lt_i32_e32 vcc, v4, v3
	v_readlane_b32 s2, v255, 45
	v_readlane_b32 s3, v255, 46
	v_cndmask_b32_e32 v4, v164, v4, vcc
	s_waitcnt lgkmcnt(0)
	v_lshlrev_b32_e32 v8, 2, v4
	v_xor_b32_e32 v4, 4, v164
	v_cmp_lt_i32_e32 vcc, v4, v3
	s_ashr_i32 s39, s38, 31
	s_lshl_b64 s[40:41], s[38:39], 2
	v_cndmask_b32_e32 v4, v164, v4, vcc
	v_lshlrev_b32_e32 v9, 2, v4
	v_xor_b32_e32 v4, 2, v164
	v_cmp_lt_i32_e32 vcc, v4, v3
	s_lshl_b64 s[42:43], s[38:39], 11
	s_mov_b64 s[44:45], 0
	v_cndmask_b32_e32 v4, v164, v4, vcc
	v_lshlrev_b32_e32 v10, 2, v4
	v_xor_b32_e32 v4, 1, v164
	v_cmp_lt_i32_e32 vcc, v4, v3
	s_nop 1
	v_cndmask_b32_e32 v3, v164, v4, vcc
	v_lshlrev_b32_e32 v11, 2, v3
	v_ashrrev_i32_e32 v3, 31, v2
	v_lshl_add_u64 v[4:5], v[2:3], 0, s[0:1]
	v_lshl_add_u64 v[2:3], v[4:5], 2, s[2:3]
	v_lshlrev_b64 v[4:5], 11, v[4:5]
	s_mov_b64 s[0:1], 0x4200000
	v_lshl_or_b32 v4, v12, 4, v4
	v_lshl_add_u64 v[2:3], v[2:3], 0, s[0:1]
	v_lshl_add_u64 v[4:5], s[2:3], 0, v[4:5]
	s_mov_b64 s[0:1], 0x400
	v_cmp_eq_u32_e32 vcc, 0, v12
	v_lshl_add_u64 v[4:5], v[4:5], 0, s[0:1]
	global_load_dwordx4 v[12:15], v[4:5], off offset:-1024
	global_load_dwordx4 v[16:19], v[4:5], off
	global_load_dword v46, v[4:5], off
	s_lshl_b64 s[100:101], s[42:43], 2
	v_mov_b32_e32 v44, v4
	v_mov_b32_e32 v45, v5
	v_lshl_add_u64 v[44:45], v[44:45], 0, s[42:43]
	global_load_dwordx4 v[48:51], v[44:45], off offset:-1024
	global_load_dwordx4 v[52:55], v[44:45], off
	global_load_dword v46, v[4:5], off
	v_lshl_add_u64 v[44:45], v[44:45], 0, s[42:43]
	global_load_dwordx4 v[56:59], v[44:45], off offset:-1024
	global_load_dwordx4 v[60:63], v[44:45], off
	global_load_dword v46, v[4:5], off
	v_lshl_add_u64 v[44:45], v[44:45], 0, s[42:43]
	global_load_dwordx4 v[64:67], v[44:45], off offset:-1024
	global_load_dwordx4 v[68:71], v[44:45], off
	global_load_dword v46, v[4:5], off
	s_branch .LBB0_31

; __device__ void phase_stat(const KP& p) {
;     ...
;   for (int row = p.bid * 8 + w; row < T_ROWS; row += p.nblk * 8) {
;     float ss = 0.f;
; #pragma unroll
;     for (int i = 0; i < 2; ++i) {
;       u32x4 v = *(const u32x4*)(hb + (size_t)row * DM + lane * 8 + 512 * i);
; #pragma unroll
;       for (int e = 0; e < 4; ++e) {
;         float a = __uint_as_float(v[e] << 16), b = __uint_as_float(v[e] & 0xffff0000u);
;         ss += a * a + b * b;
;       }
;     }
;     ss = wave_sum(ss);
;     if (lane == 0) rs[row] = rsqrtf(ss * (1.f / DM) + EPSF);
.LBB0_31:
	s_waitcnt lgkmcnt(0)
	s_waitcnt vmcnt(10)
	v_mov_b32_e32 v36, v12
	v_mov_b32_e32 v37, v13
	v_mov_b32_e32 v38, v14
	v_mov_b32_e32 v39, v15
	v_mov_b32_e32 v40, v16
	v_mov_b32_e32 v41, v17
	v_mov_b32_e32 v42, v18
	v_mov_b32_e32 v43, v19
	v_lshl_add_u64 v[44:45], v[4:5], 0, s[100:101]
	global_load_dwordx4 v[12:15], v[44:45], off offset:-1024
	global_load_dwordx4 v[16:19], v[44:45], off
	v_lshlrev_b32_e32 v20, 16, v36
	v_and_b32_e32 v36, 0xffff0000, v36
	v_lshlrev_b32_e32 v21, 16, v37
	v_and_b32_e32 v37, 0xffff0000, v37
	v_lshlrev_b32_e32 v22, 16, v38
	v_and_b32_e32 v38, 0xffff0000, v38
	v_mul_f32_e32 v36, v36, v36
	v_mul_f32_e32 v37, v37, v37
	v_lshlrev_b32_e32 v23, 16, v39
	v_and_b32_e32 v39, 0xffff0000, v39
	v_mul_f32_e32 v38, v38, v38
	v_fmac_f32_e32 v36, v20, v20
	v_fmac_f32_e32 v37, v21, v21
	v_lshlrev_b32_e32 v24, 16, v40
	v_and_b32_e32 v40, 0xffff0000, v40
	v_mul_f32_e32 v39, v39, v39
	v_fmac_f32_e32 v38, v22, v22
	v_add_f32_e32 v36, v36, v37
	v_lshlrev_b32_e32 v25, 16, v41
	v_and_b32_e32 v41, 0xffff0000, v41
	v_mul_f32_e32 v40, v40, v40
	v_fmac_f32_e32 v39, v23, v23
	v_add_f32_e32 v36, v38, v36
	v_lshlrev_b32_e32 v26, 16, v42
	v_and_b32_e32 v42, 0xffff0000, v42
	v_mul_f32_e32 v41, v41, v41
	v_fmac_f32_e32 v40, v24, v24
	v_add_f32_e32 v36, v39, v36
	v_lshlrev_b32_e32 v27, 16, v43
	v_and_b32_e32 v43, 0xffff0000, v43
	v_mul_f32_e32 v42, v42, v42
	v_fmac_f32_e32 v41, v25, v25
	v_add_f32_e32 v36, v40, v36
	v_mul_f32_e32 v43, v43, v43
	v_fmac_f32_e32 v42, v26, v26
	v_add_f32_e32 v36, v41, v36
	v_add_f32_e32 v36, v42, v36
	v_fmac_f32_e32 v43, v27, v27
	v_add_f32_e32 v36, v43, v36
	ds_bpermute_b32 v37, v6, v36
	s_waitcnt lgkmcnt(0)
	v_add_f32_e32 v36, v36, v37
	ds_bpermute_b32 v37, v7, v36
	s_waitcnt lgkmcnt(0)
	v_add_f32_e32 v36, v36, v37
	ds_bpermute_b32 v37, v8, v36
	s_waitcnt lgkmcnt(0)
	v_add_f32_e32 v36, v36, v37
	ds_bpermute_b32 v37, v9, v36
	s_waitcnt lgkmcnt(0)
	v_add_f32_e32 v36, v36, v37
	ds_bpermute_b32 v37, v10, v36
	s_waitcnt lgkmcnt(0)
	v_add_f32_e32 v36, v36, v37
	ds_bpermute_b32 v37, v11, v36
	s_and_saveexec_b64 s[46:47], vcc
	s_cbranch_execz .Lstat_adv0
	s_waitcnt lgkmcnt(0)
	v_add_f32_e32 v36, v36, v37
	v_fmamk_f32 v36, v36, 0x3a800000, v162
	s_mov_b32 s0, 0x800000
	v_mul_f32_e32 v37, 0x4b800000, v36
	v_cmp_gt_f32_e64 s[0:1], s0, v36
	s_nop 1
	v_cndmask_b32_e64 v36, v36, v37, s[0:1]
	v_rsq_f32_e32 v36, v36
	s_nop 0
	v_mul_f32_e32 v37, 0x45800000, v36
	v_cndmask_b32_e64 v36, v36, v37, s[0:1]
	global_store_dword v[2:3], v36, off

; __device__ void phase_stat(const KP& p) {
;     ...
;   for (int row = p.bid * 8 + w; row < T_ROWS; row += p.nblk * 8) {
;     float ss = 0.f;
; #pragma unroll
;     for (int i = 0; i < 2; ++i) {
;       u32x4 v = *(const u32x4*)(hb + (size_t)row * DM + lane * 8 + 512 * i);
; #pragma unroll
;       for (int e = 0; e < 4; ++e) {
;         float a = __uint_as_float(v[e] << 16), b = __uint_as_float(v[e] & 0xffff0000u);
;         ss += a * a + b * b;
;       }
;     }
;     ss = wave_sum(ss);
;     if (lane == 0) rs[row] = rsqrtf(ss * (1.f / DM) + EPSF);
.Lstat_body1:
	s_waitcnt lgkmcnt(0)
	s_waitcnt vmcnt(10)
	v_mov_b32_e32 v36, v48
	v_mov_b32_e32 v37, v49
	v_mov_b32_e32 v38, v50
	v_mov_b32_e32 v39, v51
	v_mov_b32_e32 v40, v52
	v_mov_b32_e32 v41, v53
	v_mov_b32_e32 v42, v54
	v_mov_b32_e32 v43, v55
	v_lshl_add_u64 v[44:45], v[4:5], 0, s[100:101]
	global_load_dwordx4 v[48:51], v[44:45], off offset:-1024
	global_load_dwordx4 v[52:55], v[44:45], off
	v_lshlrev_b32_e32 v20, 16, v36
	v_and_b32_e32 v36, 0xffff0000, v36
	v_lshlrev_b32_e32 v21, 16, v37
	v_and_b32_e32 v37, 0xffff0000, v37
	v_lshlrev_b32_e32 v22, 16, v38
	v_and_b32_e32 v38, 0xffff0000, v38
	v_mul_f32_e32 v36, v36, v36
	v_mul_f32_e32 v37, v37, v37
	v_lshlrev_b32_e32 v23, 16, v39
	v_and_b32_e32 v39, 0xffff0000, v39
	v_mul_f32_e32 v38, v38, v38
	v_fmac_f32_e32 v36, v20, v20
	v_fmac_f32_e32 v37, v21, v21
	v_lshlrev_b32_e32 v24, 16, v40
	v_and_b32_e32 v40, 0xffff0000, v40
	v_mul_f32_e32 v39, v39, v39
	v_fmac_f32_e32 v38, v22, v22
	v_add_f32_e32 v36, v36, v37
	v_lshlrev_b32_e32 v25, 16, v41
	v_and_b32_e32 v41, 0xffff0000, v41
	v_mul_f32_e32 v40, v40, v40
	v_fmac_f32_e32 v39, v23, v23
	v_add_f32_e32 v36, v38, v36
	v_lshlrev_b32_e32 v26, 16, v42
	v_and_b32_e32 v42, 0xffff0000, v42
	v_mul_f32_e32 v41, v41, v41
	v_fmac_f32_e32 v40, v24, v24
	v_add_f32_e32 v36, v39, v36
	v_lshlrev_b32_e32 v27, 16, v43
	v_and_b32_e32 v43, 0xffff0000, v43
	v_mul_f32_e32 v42, v42, v42
	v_fmac_f32_e32 v41, v25, v25
	v_add_f32_e32 v36, v40, v36
	v_mul_f32_e32 v43, v43, v43
	v_fmac_f32_e32 v42, v26, v26
	v_add_f32_e32 v36, v41, v36
	v_add_f32_e32 v36, v42, v36
	v_fmac_f32_e32 v43, v27, v27
	v_add_f32_e32 v36, v43, v36
	ds_bpermute_b32 v37, v6, v36
	s_waitcnt lgkmcnt(0)
	v_add_f32_e32 v36, v36, v37
	ds_bpermute_b32 v37, v7, v36
	s_waitcnt lgkmcnt(0)
	v_add_f32_e32 v36, v36, v37
	ds_bpermute_b32 v37, v8, v36
	s_waitcnt lgkmcnt(0)
	v_add_f32_e32 v36, v36, v37
	ds_bpermute_b32 v37, v9, v36
	s_waitcnt lgkmcnt(0)
	v_add_f32_e32 v36, v36, v37
	ds_bpermute_b32 v37, v10, v36
	s_waitcnt lgkmcnt(0)
	v_add_f32_e32 v36, v36, v37
	ds_bpermute_b32 v37, v11, v36
	s_and_saveexec_b64 s[46:47], vcc
	s_cbranch_execz .Lstat_adv1
	s_waitcnt lgkmcnt(0)
	v_add_f32_e32 v36, v36, v37
	v_fmamk_f32 v36, v36, 0x3a800000, v162
	s_mov_b32 s0, 0x800000
	v_mul_f32_e32 v37, 0x4b800000, v36
	v_cmp_gt_f32_e64 s[0:1], s0, v36
	s_nop 1
	v_cndmask_b32_e64 v36, v36, v37, s[0:1]
	v_rsq_f32_e32 v36, v36
	s_nop 0
	v_mul_f32_e32 v37, 0x45800000, v36
	v_cndmask_b32_e64 v36, v36, v37, s[0:1]
	global_store_dword v[2:3], v36, off

; __device__ void phase_stat(const KP& p) {
;     ...
;   for (int row = p.bid * 8 + w; row < T_ROWS; row += p.nblk * 8) {
;     float ss = 0.f;
; #pragma unroll
;     for (int i = 0; i < 2; ++i) {
;       u32x4 v = *(const u32x4*)(hb + (size_t)row * DM + lane * 8 + 512 * i);
; #pragma unroll
;       for (int e = 0; e < 4; ++e) {
;         float a = __uint_as_float(v[e] << 16), b = __uint_as_float(v[e] & 0xffff0000u);
;         ss += a * a + b * b;
;       }
;     }
;     ss = wave_sum(ss);
;     if (lane == 0) rs[row] = rsqrtf(ss * (1.f / DM) + EPSF);
.Lstat_body2:
	s_waitcnt lgkmcnt(0)
	s_waitcnt vmcnt(10)
	v_mov_b32_e32 v36, v56
	v_mov_b32_e32 v37, v57
	v_mov_b32_e32 v38, v58
	v_mov_b32_e32 v39, v59
	v_mov_b32_e32 v40, v60
	v_mov_b32_e32 v41, v61
	v_mov_b32_e32 v42, v62
	v_mov_b32_e32 v43, v63
	v_lshl_add_u64 v[44:45], v[4:5], 0, s[100:101]
	global_load_dwordx4 v[56:59], v[44:45], off offset:-1024
	global_load_dwordx4 v[60:63], v[44:45], off
	v_lshlrev_b32_e32 v20, 16, v36
	v_and_b32_e32 v36, 0xffff0000, v36
	v_lshlrev_b32_e32 v21, 16, v37
	v_and_b32_e32 v37, 0xffff0000, v37
	v_lshlrev_b32_e32 v22, 16, v38
	v_and_b32_e32 v38, 0xffff0000, v38
	v_mul_f32_e32 v36, v36, v36
	v_mul_f32_e32 v37, v37, v37
	v_lshlrev_b32_e32 v23, 16, v39
	v_and_b32_e32 v39, 0xffff0000, v39
	v_mul_f32_e32 v38, v38, v38
	v_fmac_f32_e32 v36, v20, v20
	v_fmac_f32_e32 v37, v21, v21
	v_lshlrev_b32_e32 v24, 16, v40
	v_and_b32_e32 v40, 0xffff0000, v40
	v_mul_f32_e32 v39, v39, v39
	v_fmac_f32_e32 v38, v22, v22
	v_add_f32_e32 v36, v36, v37
	v_lshlrev_b32_e32 v25, 16, v41
	v_and_b32_e32 v41, 0xffff0000, v41
	v_mul_f32_e32 v40, v40, v40
	v_fmac_f32_e32 v39, v23, v23
	v_add_f32_e32 v36, v38, v36
	v_lshlrev_b32_e32 v26, 16, v42
	v_and_b32_e32 v42, 0xffff0000, v42
	v_mul_f32_e32 v41, v41, v41
	v_fmac_f32_e32 v40, v24, v24
	v_add_f32_e32 v36, v39, v36
	v_lshlrev_b32_e32 v27, 16, v43
	v_and_b32_e32 v43, 0xffff0000, v43
	v_mul_f32_e32 v42, v42, v42
	v_fmac_f32_e32 v41, v25, v25
	v_add_f32_e32 v36, v40, v36
	v_mul_f32_e32 v43, v43, v43
	v_fmac_f32_e32 v42, v26, v26
	v_add_f32_e32 v36, v41, v36
	v_add_f32_e32 v36, v42, v36
	v_fmac_f32_e32 v43, v27, v27
	v_add_f32_e32 v36, v43, v36
	ds_bpermute_b32 v37, v6, v36
	s_waitcnt lgkmcnt(0)
	v_add_f32_e32 v36, v36, v37
	ds_bpermute_b32 v37, v7, v36
	s_waitcnt lgkmcnt(0)
	v_add_f32_e32 v36, v36, v37
	ds_bpermute_b32 v37, v8, v36
	s_waitcnt lgkmcnt(0)
	v_add_f32_e32 v36, v36, v37
	ds_bpermute_b32 v37, v9, v36
	s_waitcnt lgkmcnt(0)
	v_add_f32_e32 v36, v36, v37
	ds_bpermute_b32 v37, v10, v36
	s_waitcnt lgkmcnt(0)
	v_add_f32_e32 v36, v36, v37
	ds_bpermute_b32 v37, v11, v36
	s_and_saveexec_b64 s[46:47], vcc
	s_cbranch_execz .Lstat_adv2
	s_waitcnt lgkmcnt(0)
	v_add_f32_e32 v36, v36, v37
	v_fmamk_f32 v36, v36, 0x3a800000, v162
	s_mov_b32 s0, 0x800000
	v_mul_f32_e32 v37, 0x4b800000, v36
	v_cmp_gt_f32_e64 s[0:1], s0, v36
	s_nop 1
	v_cndmask_b32_e64 v36, v36, v37, s[0:1]
	v_rsq_f32_e32 v36, v36
	s_nop 0
	v_mul_f32_e32 v37, 0x45800000, v36
	v_cndmask_b32_e64 v36, v36, v37, s[0:1]
	global_store_dword v[2:3], v36, off

; __device__ void phase_stat(const KP& p) {
;     ...
;   for (int row = p.bid * 8 + w; row < T_ROWS; row += p.nblk * 8) {
;     float ss = 0.f;
; #pragma unroll
;     for (int i = 0; i < 2; ++i) {
;       u32x4 v = *(const u32x4*)(hb + (size_t)row * DM + lane * 8 + 512 * i);
; #pragma unroll
;       for (int e = 0; e < 4; ++e) {
;         float a = __uint_as_float(v[e] << 16), b = __uint_as_float(v[e] & 0xffff0000u);
;         ss += a * a + b * b;
;       }
;     }
;     ss = wave_sum(ss);
;     if (lane == 0) rs[row] = rsqrtf(ss * (1.f / DM) + EPSF);
;   }
.Lstat_body3:
	s_waitcnt lgkmcnt(0)
	s_waitcnt vmcnt(10)
	v_mov_b32_e32 v36, v64
	v_mov_b32_e32 v37, v65
	v_mov_b32_e32 v38, v66
	v_mov_b32_e32 v39, v67
	v_mov_b32_e32 v40, v68
	v_mov_b32_e32 v41, v69
	v_mov_b32_e32 v42, v70
	v_mov_b32_e32 v43, v71
	v_lshl_add_u64 v[44:45], v[4:5], 0, s[100:101]
	global_load_dwordx4 v[64:67], v[44:45], off offset:-1024
	global_load_dwordx4 v[68:71], v[44:45], off
	v_lshlrev_b32_e32 v20, 16, v36
	v_and_b32_e32 v36, 0xffff0000, v36
	v_lshlrev_b32_e32 v21, 16, v37
	v_and_b32_e32 v37, 0xffff0000, v37
	v_lshlrev_b32_e32 v22, 16, v38
	v_and_b32_e32 v38, 0xffff0000, v38
	v_mul_f32_e32 v36, v36, v36
	v_mul_f32_e32 v37, v37, v37
	v_lshlrev_b32_e32 v23, 16, v39
	v_and_b32_e32 v39, 0xffff0000, v39
	v_mul_f32_e32 v38, v38, v38
	v_fmac_f32_e32 v36, v20, v20
	v_fmac_f32_e32 v37, v21, v21
	v_lshlrev_b32_e32 v24, 16, v40
	v_and_b32_e32 v40, 0xffff0000, v40
	v_mul_f32_e32 v39, v39, v39
	v_fmac_f32_e32 v38, v22, v22
	v_add_f32_e32 v36, v36, v37
	v_lshlrev_b32_e32 v25, 16, v41
	v_and_b32_e32 v41, 0xffff0000, v41
	v_mul_f32_e32 v40, v40, v40
	v_fmac_f32_e32 v39, v23, v23
	v_add_f32_e32 v36, v38, v36
	v_lshlrev_b32_e32 v26, 16, v42
	v_and_b32_e32 v42, 0xffff0000, v42
	v_mul_f32_e32 v41, v41, v41
	v_fmac_f32_e32 v40, v24, v24
	v_add_f32_e32 v36, v39, v36
	v_lshlrev_b32_e32 v27, 16, v43
	v_and_b32_e32 v43, 0xffff0000, v43
	v_mul_f32_e32 v42, v42, v42
	v_fmac_f32_e32 v41, v25, v25
	v_add_f32_e32 v36, v40, v36
	v_mul_f32_e32 v43, v43, v43
	v_fmac_f32_e32 v42, v26, v26
	v_add_f32_e32 v36, v41, v36
	v_add_f32_e32 v36, v42, v36
	v_fmac_f32_e32 v43, v27, v27
	v_add_f32_e32 v36, v43, v36
	ds_bpermute_b32 v37, v6, v36
	s_waitcnt lgkmcnt(0)
	v_add_f32_e32 v36, v36, v37
	ds_bpermute_b32 v37, v7, v36
	s_waitcnt lgkmcnt(0)
	v_add_f32_e32 v36, v36, v37
	ds_bpermute_b32 v37, v8, v36
	s_waitcnt lgkmcnt(0)
	v_add_f32_e32 v36, v36, v37
	ds_bpermute_b32 v37, v9, v36
	s_waitcnt lgkmcnt(0)
	v_add_f32_e32 v36, v36, v37
	ds_bpermute_b32 v37, v10, v36
	s_waitcnt lgkmcnt(0)
	v_add_f32_e32 v36, v36, v37
	ds_bpermute_b32 v37, v11, v36
	s_and_saveexec_b64 s[46:47], vcc
	s_cbranch_execz .LBB0_30
	s_waitcnt lgkmcnt(0)
	v_add_f32_e32 v36, v36, v37
	v_fmamk_f32 v36, v36, 0x3a800000, v162
	s_mov_b32 s0, 0x800000
	v_mul_f32_e32 v37, 0x4b800000, v36
	v_cmp_gt_f32_e64 s[0:1], s0, v36
	s_nop 1
	v_cndmask_b32_e64 v36, v36, v37, s[0:1]
	v_rsq_f32_e32 v36, v36
	s_nop 0
	v_mul_f32_e32 v37, 0x45800000, v36
	v_cndmask_b32_e64 v36, v36, v37, s[0:1]
	global_store_dword v[2:3], v36, off
	s_branch .LBB0_30
